# K-start rotation phase now by XCD class (blockIdx&7, 8 phases): all workgroups inside an XCD stay in K-lockstep (L2 hits) while XCDs hit different memory-side channels
# speedup vs baseline: 1.0196x; 1.0196x over previous
.LBB0_187:
	s_lshl_b32 s28, s67, 7
	s_ashr_i32 s29, s28, 31
	s_lshl_b64 s[26:27], s[28:29], 10
	s_lshl_b64 s[6:7], s[28:29], 11
	s_add_u32 s6, s23, s6
	s_addc_u32 s7, s33, s7
	s_ashr_i32 s25, s24, 31
	s_lshl_b64 s[8:9], s[24:25], 18
	s_add_u32 s8, s56, s8
	s_addc_u32 s9, s57, s9
	v_and_b32_e32 v200, 15, v0
	v_bfe_u32 v201, v0, 4, 2
	v_and_b32_e32 v161, 7, v200
	v_xor_b32_e32 v201, v201, v161
	v_lshlrev_b32_e32 v201, 4, v201
	v_lshl_or_b32 v201, v200, 7, v201
	v_bfe_u32 v200, v0, 7, 1
	v_lshl_or_b32 v130, v200, 13, v201
	v_bfe_u32 v200, v0, 6, 1
	v_lshl_or_b32 v194, v200, 13, v201
	v_or_b32_e32 v194, 0x4000, v194
	v_xor_b32_e32 v161, 64, v130
	v_xor_b32_e32 v195, 64, v194
	v_bfe_u32 v200, v0, 3, 3
	v_and_b32_e32 v201, 7, v0
	v_xor_b32_e32 v201, v201, v200
	v_lshlrev_b32_e32 v201, 4, v201
	v_lshl_or_b32 v201, v200, 11, v201
	v_lshrrev_b32_e32 v200, 6, v0
	v_and_b32_e32 v200, 3, v200
	v_lshl_or_b32 v196, v200, 16, v201
	v_add_u32_e32 v197, 0x3c00, v196
	v_add_u32_e32 v198, 0x7800, v196
	v_add_u32_e32 v199, 0xb400, v196
	v_lshlrev_b32_e32 v200, 12, v200
	s_nop 0
	v_readfirstlane_b32 s14, v200
	s_add_u32 s14, s14, 32
	v_mov_b32_e32 v94, 0
	v_mov_b32_e32 v95, 0
	v_mov_b32_e32 v96, 0
	v_mov_b32_e32 v97, 0
	v_mov_b32_e32 v90, 0
	v_mov_b32_e32 v91, 0
	v_mov_b32_e32 v92, 0
	v_mov_b32_e32 v93, 0
	v_mov_b32_e32 v86, 0
	v_mov_b32_e32 v87, 0
	v_mov_b32_e32 v88, 0
	v_mov_b32_e32 v89, 0
	v_mov_b32_e32 v82, 0
	v_mov_b32_e32 v83, 0
	v_mov_b32_e32 v84, 0
	v_mov_b32_e32 v85, 0
	v_mov_b32_e32 v74, 0
	v_mov_b32_e32 v75, 0
	v_mov_b32_e32 v76, 0
	v_mov_b32_e32 v77, 0
	v_mov_b32_e32 v70, 0
	v_mov_b32_e32 v71, 0
	v_mov_b32_e32 v72, 0
	v_mov_b32_e32 v73, 0
	v_mov_b32_e32 v66, 0
	v_mov_b32_e32 v67, 0
	v_mov_b32_e32 v68, 0
	v_mov_b32_e32 v69, 0
	v_mov_b32_e32 v62, 0
	v_mov_b32_e32 v63, 0
	v_mov_b32_e32 v64, 0
	v_mov_b32_e32 v65, 0
	v_mov_b32_e32 v54, 0
	v_mov_b32_e32 v55, 0
	v_mov_b32_e32 v56, 0
	v_mov_b32_e32 v57, 0
	v_mov_b32_e32 v34, 0
	v_mov_b32_e32 v35, 0
	v_mov_b32_e32 v36, 0
	v_mov_b32_e32 v37, 0
	v_mov_b32_e32 v18, 0
	v_mov_b32_e32 v19, 0
	v_mov_b32_e32 v20, 0
	v_mov_b32_e32 v21, 0
	v_mov_b32_e32 v14, 0
	v_mov_b32_e32 v15, 0
	v_mov_b32_e32 v16, 0
	v_mov_b32_e32 v17, 0
	v_mov_b32_e32 v10, 0
	v_mov_b32_e32 v11, 0
	v_mov_b32_e32 v12, 0
	v_mov_b32_e32 v13, 0
	v_mov_b32_e32 v6, 0
	v_mov_b32_e32 v7, 0
	v_mov_b32_e32 v8, 0
	v_mov_b32_e32 v9, 0
	v_mov_b32_e32 v2, 0
	v_mov_b32_e32 v3, 0
	v_mov_b32_e32 v4, 0
	v_mov_b32_e32 v5, 0
	v_mov_b32_e32 v78, 0
	v_mov_b32_e32 v79, 0
	v_mov_b32_e32 v80, 0
	v_mov_b32_e32 v81, 0
	v_mov_b32_e32 v98, 0
	v_mov_b32_e32 v99, 0
	v_mov_b32_e32 v100, 0
	v_mov_b32_e32 v101, 0
	v_mov_b32_e32 v102, 0
	v_mov_b32_e32 v103, 0
	v_mov_b32_e32 v104, 0
	v_mov_b32_e32 v105, 0
	v_mov_b32_e32 v106, 0
	v_mov_b32_e32 v107, 0
	v_mov_b32_e32 v108, 0
	v_mov_b32_e32 v109, 0
	v_mov_b32_e32 v110, 0
	v_mov_b32_e32 v111, 0
	v_mov_b32_e32 v112, 0
	v_mov_b32_e32 v113, 0
	v_mov_b32_e32 v114, 0
	v_mov_b32_e32 v115, 0
	v_mov_b32_e32 v116, 0
	v_mov_b32_e32 v117, 0
	v_mov_b32_e32 v118, 0
	v_mov_b32_e32 v119, 0
	v_mov_b32_e32 v120, 0
	v_mov_b32_e32 v121, 0
	v_mov_b32_e32 v122, 0
	v_mov_b32_e32 v123, 0
	v_mov_b32_e32 v124, 0
	v_mov_b32_e32 v125, 0
	v_mov_b32_e32 v126, 0
	v_mov_b32_e32 v127, 0
	v_mov_b32_e32 v128, 0
	v_mov_b32_e32 v129, 0
	s_waitcnt lgkmcnt(0)
	s_barrier
	v_readlane_b32 s98, v255, 16
	s_and_b32 s98, s98, 7
	s_lshl_b32 s98, s98, 1
	s_lshl_b32 s99, s98, 7
	s_add_u32 s6, s6, s99
	s_addc_u32 s7, s7, 0
	s_add_u32 s8, s8, s99
	s_addc_u32 s9, s9, 0
	s_add_u32 m0, s14, 0
	s_nop 0
	global_load_lds_dwordx4 v196, s[6:7] offset:0
	global_load_lds_dwordx4 v197, s[6:7] offset:1024
	global_load_lds_dwordx4 v198, s[6:7] offset:2048
	global_load_lds_dwordx4 v199, s[6:7] offset:3072
	s_add_u32 m0, s14, 16384
	s_nop 0
	global_load_lds_dwordx4 v196, s[8:9] offset:0
	global_load_lds_dwordx4 v197, s[8:9] offset:1024
	global_load_lds_dwordx4 v198, s[8:9] offset:2048
	global_load_lds_dwordx4 v199, s[8:9] offset:3072
	s_add_u32 s98, s98, 1
	s_and_b32 s98, s98, 15
	s_cmp_eq_u32 s98, 0
	s_cselect_b32 s99, 0x800, 0
	s_add_u32 s6, s6, 0x80
	s_addc_u32 s7, s7, 0
	s_sub_u32 s6, s6, s99
	s_subb_u32 s7, s7, 0
	s_add_u32 s8, s8, 0x80
	s_addc_u32 s9, s9, 0
	s_sub_u32 s8, s8, s99
	s_subb_u32 s9, s9, 0
	s_mov_b32 s25, 0
	s_waitcnt vmcnt(0)

.LBB0_552:
	s_and_b32 s34, s33, 0xff
	s_mul_i32 s4, s34, 0xab
	s_lshr_b32 s47, s4, 11
	s_mul_i32 s4, s47, 12
	s_sub_i32 s4, s33, s4
	s_and_b32 s4, s4, 0xff
	s_lshl_b32 s4, s4, 10
	s_or_b32 s48, s4, s15
	s_lshl_b32 s35, s48, 10
	s_lshl_b32 s4, s48, 11
	s_add_u32 s10, s16, s4
	s_addc_u32 s11, s17, 0
	s_lshl_b32 s46, s47, 17
	s_lshl_b32 s4, s47, 18
	s_add_u32 s12, s18, s4
	s_addc_u32 s13, s19, 0
	v_and_b32_e32 v164, 15, v0
	v_bfe_u32 v165, v0, 4, 2
	v_and_b32_e32 v111, 7, v164
	v_xor_b32_e32 v165, v165, v111
	v_lshlrev_b32_e32 v165, 4, v165
	v_lshl_or_b32 v165, v164, 7, v165
	v_bfe_u32 v164, v0, 7, 1
	v_lshl_or_b32 v100, v164, 13, v165
	v_bfe_u32 v164, v0, 6, 1
	v_lshl_or_b32 v158, v164, 13, v165
	v_or_b32_e32 v158, 0x4000, v158
	v_xor_b32_e32 v111, 64, v100
	v_xor_b32_e32 v159, 64, v158
	v_bfe_u32 v164, v0, 3, 3
	v_and_b32_e32 v165, 7, v0
	v_xor_b32_e32 v165, v165, v164
	v_lshlrev_b32_e32 v165, 4, v165
	v_lshl_or_b32 v165, v164, 11, v165
	v_lshrrev_b32_e32 v164, 6, v0
	v_and_b32_e32 v164, 3, v164
	v_lshl_or_b32 v160, v164, 16, v165
	v_add_u32_e32 v161, 0x3c00, v160
	v_add_u32_e32 v162, 0x7800, v160
	v_add_u32_e32 v163, 0xb400, v160
	v_lshlrev_b32_e32 v164, 12, v164
	s_nop 0
	v_readfirstlane_b32 s50, v164
	s_add_u32 s50, s50, 32
	v_mov_b32_e32 v94, 0
	v_mov_b32_e32 v95, 0
	v_mov_b32_e32 v96, 0
	v_mov_b32_e32 v97, 0
	v_mov_b32_e32 v90, 0
	v_mov_b32_e32 v91, 0
	v_mov_b32_e32 v92, 0
	v_mov_b32_e32 v93, 0
	v_mov_b32_e32 v82, 0
	v_mov_b32_e32 v83, 0
	v_mov_b32_e32 v84, 0
	v_mov_b32_e32 v85, 0
	v_mov_b32_e32 v78, 0
	v_mov_b32_e32 v79, 0
	v_mov_b32_e32 v80, 0
	v_mov_b32_e32 v81, 0
	v_mov_b32_e32 v74, 0
	v_mov_b32_e32 v75, 0
	v_mov_b32_e32 v76, 0
	v_mov_b32_e32 v77, 0
	v_mov_b32_e32 v70, 0
	v_mov_b32_e32 v71, 0
	v_mov_b32_e32 v72, 0
	v_mov_b32_e32 v73, 0
	v_mov_b32_e32 v66, 0
	v_mov_b32_e32 v67, 0
	v_mov_b32_e32 v68, 0
	v_mov_b32_e32 v69, 0
	v_mov_b32_e32 v58, 0
	v_mov_b32_e32 v59, 0
	v_mov_b32_e32 v60, 0
	v_mov_b32_e32 v61, 0
	v_mov_b32_e32 v26, 0
	v_mov_b32_e32 v27, 0
	v_mov_b32_e32 v28, 0
	v_mov_b32_e32 v29, 0
	v_mov_b32_e32 v22, 0
	v_mov_b32_e32 v23, 0
	v_mov_b32_e32 v24, 0
	v_mov_b32_e32 v25, 0
	v_mov_b32_e32 v18, 0
	v_mov_b32_e32 v19, 0
	v_mov_b32_e32 v20, 0
	v_mov_b32_e32 v21, 0
	v_mov_b32_e32 v14, 0
	v_mov_b32_e32 v15, 0
	v_mov_b32_e32 v16, 0
	v_mov_b32_e32 v17, 0
	v_mov_b32_e32 v10, 0
	v_mov_b32_e32 v11, 0
	v_mov_b32_e32 v12, 0
	v_mov_b32_e32 v13, 0
	v_mov_b32_e32 v6, 0
	v_mov_b32_e32 v7, 0
	v_mov_b32_e32 v8, 0
	v_mov_b32_e32 v9, 0
	v_mov_b32_e32 v2, 0
	v_mov_b32_e32 v3, 0
	v_mov_b32_e32 v4, 0
	v_mov_b32_e32 v5, 0
	v_mov_b32_e32 v86, 0
	v_mov_b32_e32 v87, 0
	v_mov_b32_e32 v88, 0
	v_mov_b32_e32 v89, 0
	v_mov_b32_e32 v114, 0
	v_mov_b32_e32 v115, 0
	v_mov_b32_e32 v116, 0
	v_mov_b32_e32 v117, 0
	v_mov_b32_e32 v118, 0
	v_mov_b32_e32 v119, 0
	v_mov_b32_e32 v120, 0
	v_mov_b32_e32 v121, 0
	v_mov_b32_e32 v122, 0
	v_mov_b32_e32 v123, 0
	v_mov_b32_e32 v124, 0
	v_mov_b32_e32 v125, 0
	v_mov_b32_e32 v138, 0
	v_mov_b32_e32 v139, 0
	v_mov_b32_e32 v140, 0
	v_mov_b32_e32 v141, 0
	v_mov_b32_e32 v142, 0
	v_mov_b32_e32 v143, 0
	v_mov_b32_e32 v144, 0
	v_mov_b32_e32 v145, 0
	v_mov_b32_e32 v146, 0
	v_mov_b32_e32 v147, 0
	v_mov_b32_e32 v148, 0
	v_mov_b32_e32 v149, 0
	v_mov_b32_e32 v150, 0
	v_mov_b32_e32 v151, 0
	v_mov_b32_e32 v152, 0
	v_mov_b32_e32 v153, 0
	v_mov_b32_e32 v154, 0
	v_mov_b32_e32 v155, 0
	v_mov_b32_e32 v156, 0
	v_mov_b32_e32 v157, 0
	s_waitcnt lgkmcnt(0)
	s_barrier
	v_readlane_b32 s98, v255, 16
	s_and_b32 s98, s98, 7
	s_lshl_b32 s98, s98, 1
	s_lshl_b32 s99, s98, 7
	s_add_u32 s10, s10, s99
	s_addc_u32 s11, s11, 0
	s_add_u32 s12, s12, s99
	s_addc_u32 s13, s13, 0
	s_add_u32 m0, s50, 0
	s_nop 0
	global_load_lds_dwordx4 v160, s[10:11] offset:0
	global_load_lds_dwordx4 v161, s[10:11] offset:1024
	global_load_lds_dwordx4 v162, s[10:11] offset:2048
	global_load_lds_dwordx4 v163, s[10:11] offset:3072
	s_add_u32 m0, s50, 16384
	s_nop 0
	global_load_lds_dwordx4 v160, s[12:13] offset:0
	global_load_lds_dwordx4 v161, s[12:13] offset:1024
	global_load_lds_dwordx4 v162, s[12:13] offset:2048
	global_load_lds_dwordx4 v163, s[12:13] offset:3072
	s_add_u32 s98, s98, 1
	s_and_b32 s98, s98, 15
	s_cmp_eq_u32 s98, 0
	s_cselect_b32 s99, 0x800, 0
	s_add_u32 s10, s10, 0x80
	s_addc_u32 s11, s11, 0
	s_sub_u32 s10, s10, s99
	s_subb_u32 s11, s11, 0
	s_add_u32 s12, s12, 0x80
	s_addc_u32 s13, s13, 0
	s_sub_u32 s12, s12, s99
	s_subb_u32 s13, s13, 0
	s_mov_b32 s49, 0
	s_waitcnt vmcnt(0)

.LBB0_560:
	s_or_b64 exec, exec, s[10:11]
	s_lshl_b32 s10, s47, 7
	s_lshl_b32 s4, s35, 1
	s_add_u32 s12, s21, s4
	s_addc_u32 s13, s22, 0
	s_lshl_b32 s4, s46, 1
	v_mov_b32_e32 v111, v101
	s_add_u32 s46, s23, s4
	s_addc_u32 s47, s24, 0
	s_waitcnt lgkmcnt(0)
	s_barrier
	ds_read2_b32 v[26:27], v129 offset1:16
	ds_read2_b32 v[148:149], v129 offset0:132 offset1:148
	ds_read2_b32 v[28:29], v138 offset0:8 offset1:24
	ds_read2_b32 v[150:151], v138 offset0:140 offset1:156
	ds_read2_b32 v[22:23], v129 offset0:32 offset1:48
	ds_read2_b32 v[152:153], v129 offset0:164 offset1:180
	ds_read2_b32 v[24:25], v138 offset0:40 offset1:56
	ds_read2_b32 v[154:155], v138 offset0:172 offset1:188
	ds_read2_b32 v[18:19], v139 offset0:64 offset1:80
	ds_read2_b32 v[156:157], v139 offset0:196 offset1:212
	ds_read2_b32 v[20:21], v140 offset0:72 offset1:88
	ds_read2_b32 v[158:159], v140 offset0:204 offset1:220
	ds_read2_b32 v[14:15], v139 offset0:96 offset1:112
	ds_read2_b32 v[160:161], v139 offset0:228 offset1:244
	ds_read2_b32 v[16:17], v140 offset0:104 offset1:120
	ds_read2_b32 v[162:163], v140 offset0:236 offset1:252
	ds_read2_b32 v[10:11], v141 offset0:128 offset1:144
	ds_read2_b32 v[164:165], v142 offset0:4 offset1:20
	ds_read2_b32 v[12:13], v142 offset0:136 offset1:152
	ds_read2_b32 v[166:167], v143 offset0:12 offset1:28
	ds_read2_b32 v[6:7], v141 offset0:160 offset1:176
	ds_read2_b32 v[168:169], v142 offset0:36 offset1:52
	ds_read2_b32 v[8:9], v142 offset0:168 offset1:184
	ds_read2_b32 v[170:171], v143 offset0:44 offset1:60
	ds_read2_b32 v[2:3], v144 offset0:192 offset1:208
	ds_read2_b32 v[172:173], v145 offset0:68 offset1:84
	ds_read2_b32 v[4:5], v145 offset0:200 offset1:216
	ds_read2_b32 v[174:175], v146 offset0:76 offset1:92
	ds_read2_b32 v[30:31], v144 offset0:224 offset1:240
	ds_read2_b32 v[176:177], v145 offset0:100 offset1:116
	ds_read2_b32 v[32:33], v145 offset0:232 offset1:248
	ds_read2_b32 v[180:181], v146 offset0:108 offset1:124
	s_waitcnt lgkmcnt(0)
	s_barrier
	v_mov_b32_e32 v94, v31
	v_mov_b32_e32 v95, v177
	v_mov_b32_e32 v96, v33
	v_mov_b32_e32 v97, v181
	v_mov_b32_e32 v31, v176
	v_mov_b32_e32 v33, v180
	v_mov_b32_e32 v66, v3
	v_mov_b32_e32 v67, v173
	v_mov_b32_e32 v68, v5
	v_mov_b32_e32 v69, v175
	v_mov_b32_e32 v3, v172
	v_mov_b32_e32 v5, v174
	v_mov_b32_e32 v70, v7
	v_mov_b32_e32 v71, v169
	v_mov_b32_e32 v72, v9
	v_mov_b32_e32 v73, v171
	v_mov_b32_e32 v7, v168
	v_mov_b32_e32 v9, v170
	v_mov_b32_e32 v74, v11
	v_mov_b32_e32 v75, v165
	v_mov_b32_e32 v76, v13
	v_mov_b32_e32 v77, v167
	v_mov_b32_e32 v11, v164
	v_mov_b32_e32 v13, v166
	v_mov_b32_e32 v78, v15
	v_mov_b32_e32 v79, v161
	v_mov_b32_e32 v80, v17
	v_mov_b32_e32 v81, v163
	v_mov_b32_e32 v15, v160
	v_mov_b32_e32 v17, v162
	v_mov_b32_e32 v82, v19
	v_mov_b32_e32 v83, v157
	v_mov_b32_e32 v84, v21
	v_mov_b32_e32 v85, v159
	v_mov_b32_e32 v19, v156
	v_mov_b32_e32 v21, v158
	v_mov_b32_e32 v86, v23
	v_mov_b32_e32 v87, v153
	v_mov_b32_e32 v88, v25
	v_mov_b32_e32 v89, v155
	v_mov_b32_e32 v23, v152
	v_mov_b32_e32 v25, v154
	v_mov_b32_e32 v90, v27
	v_mov_b32_e32 v91, v149
	v_mov_b32_e32 v92, v29
	v_mov_b32_e32 v93, v151
	v_mov_b32_e32 v27, v148
	v_mov_b32_e32 v29, v150
	s_waitcnt lgkmcnt(0)
	s_barrier
	v_and_b32_e32 v174, 15, v0
	v_bfe_u32 v175, v0, 4, 2
	v_and_b32_e32 v111, 7, v174
	v_xor_b32_e32 v175, v175, v111
	v_lshlrev_b32_e32 v175, 4, v175
	v_lshl_or_b32 v175, v174, 7, v175
	v_bfe_u32 v174, v0, 7, 1
	v_lshl_or_b32 v100, v174, 13, v175
	v_bfe_u32 v174, v0, 6, 1
	v_lshl_or_b32 v168, v174, 13, v175
	v_or_b32_e32 v168, 0x4000, v168
	v_xor_b32_e32 v111, 64, v100
	v_xor_b32_e32 v169, 64, v168
	v_bfe_u32 v174, v0, 3, 3
	v_and_b32_e32 v175, 7, v0
	v_xor_b32_e32 v175, v175, v174
	v_lshlrev_b32_e32 v175, 4, v175
	v_lshl_or_b32 v175, v174, 11, v175
	v_lshrrev_b32_e32 v174, 6, v0
	v_and_b32_e32 v174, 3, v174
	v_lshl_or_b32 v170, v174, 16, v175
	v_add_u32_e32 v171, 0x3c00, v170
	v_add_u32_e32 v172, 0x7800, v170
	v_add_u32_e32 v173, 0xb400, v170
	v_lshlrev_b32_e32 v174, 12, v174
	s_nop 0
	v_readfirstlane_b32 s4, v174
	s_add_u32 s4, s4, 32
	v_mov_b32_e32 v116, 0
	v_mov_b32_e32 v117, 0
	v_mov_b32_e32 v118, 0
	v_mov_b32_e32 v119, 0
	v_mov_b32_e32 v120, 0
	v_mov_b32_e32 v121, 0
	v_mov_b32_e32 v122, 0
	v_mov_b32_e32 v123, 0
	v_mov_b32_e32 v124, 0
	v_mov_b32_e32 v125, 0
	v_mov_b32_e32 v126, 0
	v_mov_b32_e32 v127, 0
	v_mov_b32_e32 v148, 0
	v_mov_b32_e32 v149, 0
	v_mov_b32_e32 v150, 0
	v_mov_b32_e32 v151, 0
	v_mov_b32_e32 v152, 0
	v_mov_b32_e32 v153, 0
	v_mov_b32_e32 v154, 0
	v_mov_b32_e32 v155, 0
	v_mov_b32_e32 v156, 0
	v_mov_b32_e32 v157, 0
	v_mov_b32_e32 v158, 0
	v_mov_b32_e32 v159, 0
	v_mov_b32_e32 v160, 0
	v_mov_b32_e32 v161, 0
	v_mov_b32_e32 v162, 0
	v_mov_b32_e32 v163, 0
	v_mov_b32_e32 v164, 0
	v_mov_b32_e32 v165, 0
	v_mov_b32_e32 v166, 0
	v_mov_b32_e32 v167, 0
	s_waitcnt lgkmcnt(0)
	s_barrier
	v_readlane_b32 s98, v255, 16
	s_and_b32 s98, s98, 7
	s_lshl_b32 s98, s98, 1
	s_lshl_b32 s99, s98, 7
	s_add_u32 s12, s12, s99
	s_addc_u32 s13, s13, 0
	s_add_u32 s46, s46, s99
	s_addc_u32 s47, s47, 0
	s_add_u32 m0, s4, 0
	s_nop 0
	global_load_lds_dwordx4 v170, s[12:13] offset:0
	global_load_lds_dwordx4 v171, s[12:13] offset:1024
	global_load_lds_dwordx4 v172, s[12:13] offset:2048
	global_load_lds_dwordx4 v173, s[12:13] offset:3072
	s_add_u32 m0, s4, 16384
	s_nop 0
	global_load_lds_dwordx4 v170, s[46:47] offset:0
	global_load_lds_dwordx4 v171, s[46:47] offset:1024
	global_load_lds_dwordx4 v172, s[46:47] offset:2048
	global_load_lds_dwordx4 v173, s[46:47] offset:3072
	s_add_u32 s98, s98, 1
	s_and_b32 s98, s98, 15
	s_cmp_eq_u32 s98, 0
	s_cselect_b32 s99, 0x800, 0
	s_add_u32 s12, s12, 0x80
	s_addc_u32 s13, s13, 0
	s_sub_u32 s12, s12, s99
	s_subb_u32 s13, s13, 0
	s_add_u32 s46, s46, 0x80
	s_addc_u32 s47, s47, 0
	s_sub_u32 s46, s46, s99
	s_subb_u32 s47, s47, 0
	s_mov_b32 s11, 0
	s_waitcnt vmcnt(0)

.LBB0_634:
	s_and_b32 s31, s30, 0xff
	s_mul_i32 s4, s31, 0xab
	s_lshr_b32 s33, s4, 11
	s_mul_i32 s4, s33, 12
	s_sub_i32 s4, s30, s4
	s_and_b32 s4, s4, 0xff
	s_lshl_b32 s4, s4, 21
	s_or_b32 s4, s4, s23
	s_add_u32 s14, s18, s4
	s_addc_u32 s15, s19, 0
	s_lshl_b32 s4, s33, 18
	s_add_u32 s16, s20, s4
	s_addc_u32 s17, s21, 0
	v_and_b32_e32 v162, 15, v0
	v_bfe_u32 v163, v0, 4, 2
	v_and_b32_e32 v109, 7, v162
	v_xor_b32_e32 v163, v163, v109
	v_lshlrev_b32_e32 v163, 4, v163
	v_lshl_or_b32 v163, v162, 7, v163
	v_bfe_u32 v162, v0, 7, 1
	v_lshl_or_b32 v100, v162, 13, v163
	v_bfe_u32 v162, v0, 6, 1
	v_lshl_or_b32 v156, v162, 13, v163
	v_or_b32_e32 v156, 0x4000, v156
	v_xor_b32_e32 v109, 64, v100
	v_xor_b32_e32 v157, 64, v156
	v_bfe_u32 v162, v0, 3, 3
	v_and_b32_e32 v163, 7, v0
	v_xor_b32_e32 v163, v163, v162
	v_lshlrev_b32_e32 v163, 4, v163
	v_lshl_or_b32 v163, v162, 11, v163
	v_lshrrev_b32_e32 v162, 6, v0
	v_and_b32_e32 v162, 3, v162
	v_lshl_or_b32 v158, v162, 16, v163
	v_add_u32_e32 v159, 0x3c00, v158
	v_add_u32_e32 v160, 0x7800, v158
	v_add_u32_e32 v161, 0xb400, v158
	v_lshlrev_b32_e32 v162, 12, v162
	s_nop 0
	v_readfirstlane_b32 s35, v162
	s_add_u32 s35, s35, 32
	v_mov_b32_e32 v94, 0
	v_mov_b32_e32 v95, 0
	v_mov_b32_e32 v96, 0
	v_mov_b32_e32 v97, 0
	v_mov_b32_e32 v90, 0
	v_mov_b32_e32 v91, 0
	v_mov_b32_e32 v92, 0
	v_mov_b32_e32 v93, 0
	v_mov_b32_e32 v82, 0
	v_mov_b32_e32 v83, 0
	v_mov_b32_e32 v84, 0
	v_mov_b32_e32 v85, 0
	v_mov_b32_e32 v78, 0
	v_mov_b32_e32 v79, 0
	v_mov_b32_e32 v80, 0
	v_mov_b32_e32 v81, 0
	v_mov_b32_e32 v74, 0
	v_mov_b32_e32 v75, 0
	v_mov_b32_e32 v76, 0
	v_mov_b32_e32 v77, 0
	v_mov_b32_e32 v70, 0
	v_mov_b32_e32 v71, 0
	v_mov_b32_e32 v72, 0
	v_mov_b32_e32 v73, 0
	v_mov_b32_e32 v66, 0
	v_mov_b32_e32 v67, 0
	v_mov_b32_e32 v68, 0
	v_mov_b32_e32 v69, 0
	v_mov_b32_e32 v62, 0
	v_mov_b32_e32 v63, 0
	v_mov_b32_e32 v64, 0
	v_mov_b32_e32 v65, 0
	v_mov_b32_e32 v34, 0
	v_mov_b32_e32 v35, 0
	v_mov_b32_e32 v36, 0
	v_mov_b32_e32 v37, 0
	v_mov_b32_e32 v26, 0
	v_mov_b32_e32 v27, 0
	v_mov_b32_e32 v28, 0
	v_mov_b32_e32 v29, 0
	v_mov_b32_e32 v18, 0
	v_mov_b32_e32 v19, 0
	v_mov_b32_e32 v20, 0
	v_mov_b32_e32 v21, 0
	v_mov_b32_e32 v14, 0
	v_mov_b32_e32 v15, 0
	v_mov_b32_e32 v16, 0
	v_mov_b32_e32 v17, 0
	v_mov_b32_e32 v10, 0
	v_mov_b32_e32 v11, 0
	v_mov_b32_e32 v12, 0
	v_mov_b32_e32 v13, 0
	v_mov_b32_e32 v6, 0
	v_mov_b32_e32 v7, 0
	v_mov_b32_e32 v8, 0
	v_mov_b32_e32 v9, 0
	v_mov_b32_e32 v2, 0
	v_mov_b32_e32 v3, 0
	v_mov_b32_e32 v4, 0
	v_mov_b32_e32 v5, 0
	v_mov_b32_e32 v86, 0
	v_mov_b32_e32 v87, 0
	v_mov_b32_e32 v88, 0
	v_mov_b32_e32 v89, 0
	v_mov_b32_e32 v110, 0
	v_mov_b32_e32 v111, 0
	v_mov_b32_e32 v112, 0
	v_mov_b32_e32 v113, 0
	v_mov_b32_e32 v114, 0
	v_mov_b32_e32 v115, 0
	v_mov_b32_e32 v116, 0
	v_mov_b32_e32 v117, 0
	v_mov_b32_e32 v118, 0
	v_mov_b32_e32 v119, 0
	v_mov_b32_e32 v120, 0
	v_mov_b32_e32 v121, 0
	v_mov_b32_e32 v136, 0
	v_mov_b32_e32 v137, 0
	v_mov_b32_e32 v138, 0
	v_mov_b32_e32 v139, 0
	v_mov_b32_e32 v140, 0
	v_mov_b32_e32 v141, 0
	v_mov_b32_e32 v142, 0
	v_mov_b32_e32 v143, 0
	v_mov_b32_e32 v144, 0
	v_mov_b32_e32 v145, 0
	v_mov_b32_e32 v146, 0
	v_mov_b32_e32 v147, 0
	v_mov_b32_e32 v148, 0
	v_mov_b32_e32 v149, 0
	v_mov_b32_e32 v150, 0
	v_mov_b32_e32 v151, 0
	v_mov_b32_e32 v152, 0
	v_mov_b32_e32 v153, 0
	v_mov_b32_e32 v154, 0
	v_mov_b32_e32 v155, 0
	s_waitcnt lgkmcnt(0)
	s_barrier
	v_readlane_b32 s98, v255, 16
	s_and_b32 s98, s98, 7
	s_lshl_b32 s98, s98, 1
	s_lshl_b32 s99, s98, 7
	s_add_u32 s14, s14, s99
	s_addc_u32 s15, s15, 0
	s_add_u32 s16, s16, s99
	s_addc_u32 s17, s17, 0
	s_add_u32 m0, s35, 0
	s_nop 0
	global_load_lds_dwordx4 v158, s[14:15] offset:0
	global_load_lds_dwordx4 v159, s[14:15] offset:1024
	global_load_lds_dwordx4 v160, s[14:15] offset:2048
	global_load_lds_dwordx4 v161, s[14:15] offset:3072
	s_add_u32 m0, s35, 16384
	s_nop 0
	global_load_lds_dwordx4 v158, s[16:17] offset:0
	global_load_lds_dwordx4 v159, s[16:17] offset:1024
	global_load_lds_dwordx4 v160, s[16:17] offset:2048
	global_load_lds_dwordx4 v161, s[16:17] offset:3072
	s_add_u32 s98, s98, 1
	s_and_b32 s98, s98, 15
	s_cmp_eq_u32 s98, 0
	s_cselect_b32 s99, 0x800, 0
	s_add_u32 s14, s14, 0x80
	s_addc_u32 s15, s15, 0
	s_sub_u32 s14, s14, s99
	s_subb_u32 s15, s15, 0
	s_add_u32 s16, s16, 0x80
	s_addc_u32 s17, s17, 0
	s_sub_u32 s16, s16, s99
	s_subb_u32 s17, s17, 0
	s_mov_b32 s34, 0
	s_waitcnt vmcnt(0)

.LBB0_786:
	s_lshl_b32 s10, s48, 7
	s_xor_b64 s[46:47], s[50:51], -1
	s_or_b32 s50, s31, s10
	s_mov_b32 s51, s75
	s_lshl_b64 s[50:51], s[50:51], 11
	s_add_u32 s50, s54, s50
	s_addc_u32 s51, s55, s51
	s_waitcnt lgkmcnt(0)
	s_lshl_b32 s98, s30, 11
	s_add_u32 s98, s52, s98
	s_addc_u32 s99, s53, 0
	v_and_b32_e32 v222, 15, v0
	v_bfe_u32 v223, v0, 4, 2
	v_and_b32_e32 v141, 7, v222
	v_xor_b32_e32 v223, v223, v141
	v_lshlrev_b32_e32 v223, 4, v223
	v_lshl_or_b32 v223, v222, 7, v223
	v_bfe_u32 v222, v0, 7, 1
	v_lshl_or_b32 v140, v222, 13, v223
	v_bfe_u32 v222, v0, 6, 1
	v_lshl_or_b32 v216, v222, 13, v223
	v_or_b32_e32 v216, 0x4000, v216
	v_xor_b32_e32 v141, 64, v140
	v_xor_b32_e32 v217, 64, v216
	v_bfe_u32 v222, v0, 3, 3
	v_and_b32_e32 v223, 7, v0
	v_xor_b32_e32 v223, v223, v222
	v_lshlrev_b32_e32 v223, 4, v223
	v_lshl_or_b32 v223, v222, 11, v223
	v_lshrrev_b32_e32 v222, 6, v0
	v_and_b32_e32 v222, 3, v222
	v_lshl_or_b32 v218, v222, 16, v223
	v_add_u32_e32 v219, 0x3c00, v218
	v_add_u32_e32 v220, 0x7800, v218
	v_add_u32_e32 v221, 0xb400, v218
	v_lshlrev_b32_e32 v222, 12, v222
	s_nop 0
	v_readfirstlane_b32 s101, v222
	s_add_u32 s101, s101, 32
	v_mov_b32_e32 v86, 0
	v_mov_b32_e32 v87, 0
	v_mov_b32_e32 v88, 0
	v_mov_b32_e32 v89, 0
	v_mov_b32_e32 v82, 0
	v_mov_b32_e32 v83, 0
	v_mov_b32_e32 v84, 0
	v_mov_b32_e32 v85, 0
	v_mov_b32_e32 v78, 0
	v_mov_b32_e32 v79, 0
	v_mov_b32_e32 v80, 0
	v_mov_b32_e32 v81, 0
	v_mov_b32_e32 v74, 0
	v_mov_b32_e32 v75, 0
	v_mov_b32_e32 v76, 0
	v_mov_b32_e32 v77, 0
	v_mov_b32_e32 v70, 0
	v_mov_b32_e32 v71, 0
	v_mov_b32_e32 v72, 0
	v_mov_b32_e32 v73, 0
	v_mov_b32_e32 v90, 0
	v_mov_b32_e32 v91, 0
	v_mov_b32_e32 v92, 0
	v_mov_b32_e32 v93, 0
	v_mov_b32_e32 v94, 0
	v_mov_b32_e32 v95, 0
	v_mov_b32_e32 v96, 0
	v_mov_b32_e32 v97, 0
	v_mov_b32_e32 v6, 0
	v_mov_b32_e32 v7, 0
	v_mov_b32_e32 v8, 0
	v_mov_b32_e32 v9, 0
	v_mov_b32_e32 v2, 0
	v_mov_b32_e32 v3, 0
	v_mov_b32_e32 v4, 0
	v_mov_b32_e32 v5, 0
	v_mov_b32_e32 v10, 0
	v_mov_b32_e32 v11, 0
	v_mov_b32_e32 v12, 0
	v_mov_b32_e32 v13, 0
	v_mov_b32_e32 v14, 0
	v_mov_b32_e32 v15, 0
	v_mov_b32_e32 v16, 0
	v_mov_b32_e32 v17, 0
	v_mov_b32_e32 v26, 0
	v_mov_b32_e32 v27, 0
	v_mov_b32_e32 v28, 0
	v_mov_b32_e32 v29, 0
	v_mov_b32_e32 v34, 0
	v_mov_b32_e32 v35, 0
	v_mov_b32_e32 v36, 0
	v_mov_b32_e32 v37, 0
	v_mov_b32_e32 v30, 0
	v_mov_b32_e32 v31, 0
	v_mov_b32_e32 v32, 0
	v_mov_b32_e32 v33, 0
	v_mov_b32_e32 v22, 0
	v_mov_b32_e32 v23, 0
	v_mov_b32_e32 v24, 0
	v_mov_b32_e32 v25, 0
	v_mov_b32_e32 v18, 0
	v_mov_b32_e32 v19, 0
	v_mov_b32_e32 v20, 0
	v_mov_b32_e32 v21, 0
	v_mov_b32_e32 v136, 0
	v_mov_b32_e32 v137, 0
	v_mov_b32_e32 v138, 0
	v_mov_b32_e32 v139, 0
	v_mov_b32_e32 v188, 0
	v_mov_b32_e32 v189, 0
	v_mov_b32_e32 v190, 0
	v_mov_b32_e32 v191, 0
	v_mov_b32_e32 v192, 0
	v_mov_b32_e32 v193, 0
	v_mov_b32_e32 v194, 0
	v_mov_b32_e32 v195, 0
	v_mov_b32_e32 v196, 0
	v_mov_b32_e32 v197, 0
	v_mov_b32_e32 v198, 0
	v_mov_b32_e32 v199, 0
	v_mov_b32_e32 v200, 0
	v_mov_b32_e32 v201, 0
	v_mov_b32_e32 v202, 0
	v_mov_b32_e32 v203, 0
	v_mov_b32_e32 v204, 0
	v_mov_b32_e32 v205, 0
	v_mov_b32_e32 v206, 0
	v_mov_b32_e32 v207, 0
	v_mov_b32_e32 v208, 0
	v_mov_b32_e32 v209, 0
	v_mov_b32_e32 v210, 0
	v_mov_b32_e32 v211, 0
	v_mov_b32_e32 v212, 0
	v_mov_b32_e32 v213, 0
	v_mov_b32_e32 v214, 0
	v_mov_b32_e32 v215, 0
	s_waitcnt lgkmcnt(0)
	s_barrier
	v_readlane_b32 s49, v255, 16
	s_and_b32 s49, s49, 7
	s_lshl_b32 s49, s49, 1
	s_lshl_b32 s10, s49, 7
	s_add_u32 s98, s98, s10
	s_addc_u32 s99, s99, 0
	s_add_u32 s50, s50, s10
	s_addc_u32 s51, s51, 0
	s_add_u32 m0, s101, 0
	s_nop 0
	global_load_lds_dwordx4 v218, s[98:99] offset:0
	global_load_lds_dwordx4 v219, s[98:99] offset:1024
	global_load_lds_dwordx4 v220, s[98:99] offset:2048
	global_load_lds_dwordx4 v221, s[98:99] offset:3072
	s_add_u32 m0, s101, 16384
	s_nop 0
	global_load_lds_dwordx4 v218, s[50:51] offset:0
	global_load_lds_dwordx4 v219, s[50:51] offset:1024
	global_load_lds_dwordx4 v220, s[50:51] offset:2048
	global_load_lds_dwordx4 v221, s[50:51] offset:3072
	s_add_u32 s49, s49, 1
	s_and_b32 s49, s49, 15
	s_cmp_eq_u32 s49, 0
	s_cselect_b32 s10, 0x800, 0
	s_add_u32 s98, s98, 0x80
	s_addc_u32 s99, s99, 0
	s_sub_u32 s98, s98, s10
	s_subb_u32 s99, s99, 0
	s_add_u32 s50, s50, 0x80
	s_addc_u32 s51, s51, 0
	s_sub_u32 s50, s50, s10
	s_subb_u32 s51, s51, 0
	s_mov_b32 s100, 0
	s_waitcnt vmcnt(0)

.LBB0_927:
	s_lshl_b32 s28, s66, 7
	s_ashr_i32 s29, s28, 31
	s_lshl_b64 s[26:27], s[28:29], 10
	s_lshl_b64 s[6:7], s[28:29], 11
	s_add_u32 s6, s23, s6
	s_addc_u32 s7, s33, s7
	s_ashr_i32 s25, s24, 31
	s_lshl_b64 s[8:9], s[24:25], 18
	s_add_u32 s8, s54, s8
	s_addc_u32 s9, s55, s9
	v_and_b32_e32 v200, 15, v0
	v_bfe_u32 v201, v0, 4, 2
	v_and_b32_e32 v163, 7, v200
	v_xor_b32_e32 v201, v201, v163
	v_lshlrev_b32_e32 v201, 4, v201
	v_lshl_or_b32 v201, v200, 7, v201
	v_bfe_u32 v200, v0, 7, 1
	v_lshl_or_b32 v132, v200, 13, v201
	v_bfe_u32 v200, v0, 6, 1
	v_lshl_or_b32 v194, v200, 13, v201
	v_or_b32_e32 v194, 0x4000, v194
	v_xor_b32_e32 v163, 64, v132
	v_xor_b32_e32 v195, 64, v194
	v_bfe_u32 v200, v0, 3, 3
	v_and_b32_e32 v201, 7, v0
	v_xor_b32_e32 v201, v201, v200
	v_lshlrev_b32_e32 v201, 4, v201
	v_lshl_or_b32 v201, v200, 11, v201
	v_lshrrev_b32_e32 v200, 6, v0
	v_and_b32_e32 v200, 3, v200
	v_lshl_or_b32 v196, v200, 16, v201
	v_add_u32_e32 v197, 0x3c00, v196
	v_add_u32_e32 v198, 0x7800, v196
	v_add_u32_e32 v199, 0xb400, v196
	v_lshlrev_b32_e32 v200, 12, v200
	s_nop 0
	v_readfirstlane_b32 s14, v200
	s_add_u32 s14, s14, 32
	v_mov_b32_e32 v94, 0
	v_mov_b32_e32 v95, 0
	v_mov_b32_e32 v96, 0
	v_mov_b32_e32 v97, 0
	v_mov_b32_e32 v90, 0
	v_mov_b32_e32 v91, 0
	v_mov_b32_e32 v92, 0
	v_mov_b32_e32 v93, 0
	v_mov_b32_e32 v86, 0
	v_mov_b32_e32 v87, 0
	v_mov_b32_e32 v88, 0
	v_mov_b32_e32 v89, 0
	v_mov_b32_e32 v82, 0
	v_mov_b32_e32 v83, 0
	v_mov_b32_e32 v84, 0
	v_mov_b32_e32 v85, 0
	v_mov_b32_e32 v74, 0
	v_mov_b32_e32 v75, 0
	v_mov_b32_e32 v76, 0
	v_mov_b32_e32 v77, 0
	v_mov_b32_e32 v70, 0
	v_mov_b32_e32 v71, 0
	v_mov_b32_e32 v72, 0
	v_mov_b32_e32 v73, 0
	v_mov_b32_e32 v66, 0
	v_mov_b32_e32 v67, 0
	v_mov_b32_e32 v68, 0
	v_mov_b32_e32 v69, 0
	v_mov_b32_e32 v62, 0
	v_mov_b32_e32 v63, 0
	v_mov_b32_e32 v64, 0
	v_mov_b32_e32 v65, 0
	v_mov_b32_e32 v50, 0
	v_mov_b32_e32 v51, 0
	v_mov_b32_e32 v52, 0
	v_mov_b32_e32 v53, 0
	v_mov_b32_e32 v30, 0
	v_mov_b32_e32 v31, 0
	v_mov_b32_e32 v32, 0
	v_mov_b32_e32 v33, 0
	v_mov_b32_e32 v18, 0
	v_mov_b32_e32 v19, 0
	v_mov_b32_e32 v20, 0
	v_mov_b32_e32 v21, 0
	v_mov_b32_e32 v14, 0
	v_mov_b32_e32 v15, 0
	v_mov_b32_e32 v16, 0
	v_mov_b32_e32 v17, 0
	v_mov_b32_e32 v10, 0
	v_mov_b32_e32 v11, 0
	v_mov_b32_e32 v12, 0
	v_mov_b32_e32 v13, 0
	v_mov_b32_e32 v6, 0
	v_mov_b32_e32 v7, 0
	v_mov_b32_e32 v8, 0
	v_mov_b32_e32 v9, 0
	v_mov_b32_e32 v2, 0
	v_mov_b32_e32 v3, 0
	v_mov_b32_e32 v4, 0
	v_mov_b32_e32 v5, 0
	v_mov_b32_e32 v78, 0
	v_mov_b32_e32 v79, 0
	v_mov_b32_e32 v80, 0
	v_mov_b32_e32 v81, 0
	v_mov_b32_e32 v98, 0
	v_mov_b32_e32 v99, 0
	v_mov_b32_e32 v100, 0
	v_mov_b32_e32 v101, 0
	v_mov_b32_e32 v102, 0
	v_mov_b32_e32 v103, 0
	v_mov_b32_e32 v104, 0
	v_mov_b32_e32 v105, 0
	v_mov_b32_e32 v106, 0
	v_mov_b32_e32 v107, 0
	v_mov_b32_e32 v108, 0
	v_mov_b32_e32 v109, 0
	v_mov_b32_e32 v110, 0
	v_mov_b32_e32 v111, 0
	v_mov_b32_e32 v112, 0
	v_mov_b32_e32 v113, 0
	v_mov_b32_e32 v114, 0
	v_mov_b32_e32 v115, 0
	v_mov_b32_e32 v116, 0
	v_mov_b32_e32 v117, 0
	v_mov_b32_e32 v118, 0
	v_mov_b32_e32 v119, 0
	v_mov_b32_e32 v120, 0
	v_mov_b32_e32 v121, 0
	v_mov_b32_e32 v122, 0
	v_mov_b32_e32 v123, 0
	v_mov_b32_e32 v124, 0
	v_mov_b32_e32 v125, 0
	v_mov_b32_e32 v126, 0
	v_mov_b32_e32 v127, 0
	v_mov_b32_e32 v128, 0
	v_mov_b32_e32 v129, 0
	s_waitcnt lgkmcnt(0)
	s_barrier
	v_readlane_b32 s98, v255, 16
	s_and_b32 s98, s98, 7
	s_lshl_b32 s98, s98, 1
	s_lshl_b32 s99, s98, 7
	s_add_u32 s6, s6, s99
	s_addc_u32 s7, s7, 0
	s_add_u32 s8, s8, s99
	s_addc_u32 s9, s9, 0
	s_add_u32 m0, s14, 0
	s_nop 0
	global_load_lds_dwordx4 v196, s[6:7] offset:0
	global_load_lds_dwordx4 v197, s[6:7] offset:1024
	global_load_lds_dwordx4 v198, s[6:7] offset:2048
	global_load_lds_dwordx4 v199, s[6:7] offset:3072
	s_add_u32 m0, s14, 16384
	s_nop 0
	global_load_lds_dwordx4 v196, s[8:9] offset:0
	global_load_lds_dwordx4 v197, s[8:9] offset:1024
	global_load_lds_dwordx4 v198, s[8:9] offset:2048
	global_load_lds_dwordx4 v199, s[8:9] offset:3072
	s_add_u32 s98, s98, 1
	s_and_b32 s98, s98, 15
	s_cmp_eq_u32 s98, 0
	s_cselect_b32 s99, 0x800, 0
	s_add_u32 s6, s6, 0x80
	s_addc_u32 s7, s7, 0
	s_sub_u32 s6, s6, s99
	s_subb_u32 s7, s7, 0
	s_add_u32 s8, s8, 0x80
	s_addc_u32 s9, s9, 0
	s_sub_u32 s8, s8, s99
	s_subb_u32 s9, s9, 0
	s_mov_b32 s25, 0
	s_waitcnt vmcnt(0)

.LBB0_1292:
	s_and_b32 s70, s69, 0xff
	s_mul_i32 s4, s70, 0xab
	s_lshr_b32 s73, s4, 11
	s_mul_i32 s4, s73, 12
	s_sub_i32 s4, s69, s4
	s_and_b32 s4, s4, 0xff
	s_lshl_b32 s4, s4, 10
	s_or_b32 s8, s4, s52
	s_lshl_b32 s71, s8, 10
	s_lshl_b32 s4, s8, 11
	s_add_u32 s4, s53, s4
	s_addc_u32 s5, s54, 0
	s_lshl_b32 s6, s73, 17
	s_add_i32 s72, s6, 0x100000
	s_lshl_b32 s6, s72, 1
	s_add_u32 s6, s55, s6
	s_addc_u32 s7, s56, 0
	v_and_b32_e32 v164, 15, v0
	v_bfe_u32 v165, v0, 4, 2
	v_and_b32_e32 v111, 7, v164
	v_xor_b32_e32 v165, v165, v111
	v_lshlrev_b32_e32 v165, 4, v165
	v_lshl_or_b32 v165, v164, 7, v165
	v_bfe_u32 v164, v0, 7, 1
	v_lshl_or_b32 v100, v164, 13, v165
	v_bfe_u32 v164, v0, 6, 1
	v_lshl_or_b32 v158, v164, 13, v165
	v_or_b32_e32 v158, 0x4000, v158
	v_xor_b32_e32 v111, 64, v100
	v_xor_b32_e32 v159, 64, v158
	v_bfe_u32 v164, v0, 3, 3
	v_and_b32_e32 v165, 7, v0
	v_xor_b32_e32 v165, v165, v164
	v_lshlrev_b32_e32 v165, 4, v165
	v_lshl_or_b32 v165, v164, 11, v165
	v_lshrrev_b32_e32 v164, 6, v0
	v_and_b32_e32 v164, 3, v164
	v_lshl_or_b32 v160, v164, 16, v165
	v_add_u32_e32 v161, 0x3c00, v160
	v_add_u32_e32 v162, 0x7800, v160
	v_add_u32_e32 v163, 0xb400, v160
	v_lshlrev_b32_e32 v164, 12, v164
	s_nop 0
	v_readfirstlane_b32 s10, v164
	s_add_u32 s10, s10, 32
	v_mov_b32_e32 v94, 0
	v_mov_b32_e32 v95, 0
	v_mov_b32_e32 v96, 0
	v_mov_b32_e32 v97, 0
	v_mov_b32_e32 v90, 0
	v_mov_b32_e32 v91, 0
	v_mov_b32_e32 v92, 0
	v_mov_b32_e32 v93, 0
	v_mov_b32_e32 v82, 0
	v_mov_b32_e32 v83, 0
	v_mov_b32_e32 v84, 0
	v_mov_b32_e32 v85, 0
	v_mov_b32_e32 v78, 0
	v_mov_b32_e32 v79, 0
	v_mov_b32_e32 v80, 0
	v_mov_b32_e32 v81, 0
	v_mov_b32_e32 v74, 0
	v_mov_b32_e32 v75, 0
	v_mov_b32_e32 v76, 0
	v_mov_b32_e32 v77, 0
	v_mov_b32_e32 v70, 0
	v_mov_b32_e32 v71, 0
	v_mov_b32_e32 v72, 0
	v_mov_b32_e32 v73, 0
	v_mov_b32_e32 v66, 0
	v_mov_b32_e32 v67, 0
	v_mov_b32_e32 v68, 0
	v_mov_b32_e32 v69, 0
	v_mov_b32_e32 v58, 0
	v_mov_b32_e32 v59, 0
	v_mov_b32_e32 v60, 0
	v_mov_b32_e32 v61, 0
	v_mov_b32_e32 v26, 0
	v_mov_b32_e32 v27, 0
	v_mov_b32_e32 v28, 0
	v_mov_b32_e32 v29, 0
	v_mov_b32_e32 v22, 0
	v_mov_b32_e32 v23, 0
	v_mov_b32_e32 v24, 0
	v_mov_b32_e32 v25, 0
	v_mov_b32_e32 v18, 0
	v_mov_b32_e32 v19, 0
	v_mov_b32_e32 v20, 0
	v_mov_b32_e32 v21, 0
	v_mov_b32_e32 v14, 0
	v_mov_b32_e32 v15, 0
	v_mov_b32_e32 v16, 0
	v_mov_b32_e32 v17, 0
	v_mov_b32_e32 v10, 0
	v_mov_b32_e32 v11, 0
	v_mov_b32_e32 v12, 0
	v_mov_b32_e32 v13, 0
	v_mov_b32_e32 v6, 0
	v_mov_b32_e32 v7, 0
	v_mov_b32_e32 v8, 0
	v_mov_b32_e32 v9, 0
	v_mov_b32_e32 v2, 0
	v_mov_b32_e32 v3, 0
	v_mov_b32_e32 v4, 0
	v_mov_b32_e32 v5, 0
	v_mov_b32_e32 v86, 0
	v_mov_b32_e32 v87, 0
	v_mov_b32_e32 v88, 0
	v_mov_b32_e32 v89, 0
	v_mov_b32_e32 v114, 0
	v_mov_b32_e32 v115, 0
	v_mov_b32_e32 v116, 0
	v_mov_b32_e32 v117, 0
	v_mov_b32_e32 v118, 0
	v_mov_b32_e32 v119, 0
	v_mov_b32_e32 v120, 0
	v_mov_b32_e32 v121, 0
	v_mov_b32_e32 v122, 0
	v_mov_b32_e32 v123, 0
	v_mov_b32_e32 v124, 0
	v_mov_b32_e32 v125, 0
	v_mov_b32_e32 v138, 0
	v_mov_b32_e32 v139, 0
	v_mov_b32_e32 v140, 0
	v_mov_b32_e32 v141, 0
	v_mov_b32_e32 v142, 0
	v_mov_b32_e32 v143, 0
	v_mov_b32_e32 v144, 0
	v_mov_b32_e32 v145, 0
	v_mov_b32_e32 v146, 0
	v_mov_b32_e32 v147, 0
	v_mov_b32_e32 v148, 0
	v_mov_b32_e32 v149, 0
	v_mov_b32_e32 v150, 0
	v_mov_b32_e32 v151, 0
	v_mov_b32_e32 v152, 0
	v_mov_b32_e32 v153, 0
	v_mov_b32_e32 v154, 0
	v_mov_b32_e32 v155, 0
	v_mov_b32_e32 v156, 0
	v_mov_b32_e32 v157, 0
	s_waitcnt lgkmcnt(0)
	s_barrier
	v_readlane_b32 s98, v255, 16
	s_and_b32 s98, s98, 7
	s_lshl_b32 s98, s98, 1
	s_lshl_b32 s99, s98, 7
	s_add_u32 s4, s4, s99
	s_addc_u32 s5, s5, 0
	s_add_u32 s6, s6, s99
	s_addc_u32 s7, s7, 0
	s_add_u32 m0, s10, 0
	s_nop 0
	global_load_lds_dwordx4 v160, s[4:5] offset:0
	global_load_lds_dwordx4 v161, s[4:5] offset:1024
	global_load_lds_dwordx4 v162, s[4:5] offset:2048
	global_load_lds_dwordx4 v163, s[4:5] offset:3072
	s_add_u32 m0, s10, 16384
	s_nop 0
	global_load_lds_dwordx4 v160, s[6:7] offset:0
	global_load_lds_dwordx4 v161, s[6:7] offset:1024
	global_load_lds_dwordx4 v162, s[6:7] offset:2048
	global_load_lds_dwordx4 v163, s[6:7] offset:3072
	s_add_u32 s98, s98, 1
	s_and_b32 s98, s98, 15
	s_cmp_eq_u32 s98, 0
	s_cselect_b32 s99, 0x800, 0
	s_add_u32 s4, s4, 0x80
	s_addc_u32 s5, s5, 0
	s_sub_u32 s4, s4, s99
	s_subb_u32 s5, s5, 0
	s_add_u32 s6, s6, 0x80
	s_addc_u32 s7, s7, 0
	s_sub_u32 s6, s6, s99
	s_subb_u32 s7, s7, 0
	s_mov_b32 s9, 0
	s_waitcnt vmcnt(0)

.LBB0_1300:
	s_or_b64 exec, exec, s[50:51]
	s_lshl_b32 s4, s73, 7
	s_lshl_b32 s5, s71, 1
	s_add_u32 s6, s58, s5
	s_addc_u32 s7, s59, 0
	s_lshl_b32 s5, s72, 1
	v_mov_b32_e32 v111, v101
	s_add_u32 s8, s60, s5
	s_addc_u32 s9, s61, 0
	s_waitcnt lgkmcnt(0)
	s_barrier
	ds_read2_b32 v[26:27], v129 offset1:16
	ds_read2_b32 v[148:149], v129 offset0:132 offset1:148
	ds_read2_b32 v[28:29], v138 offset0:8 offset1:24
	ds_read2_b32 v[150:151], v138 offset0:140 offset1:156
	ds_read2_b32 v[22:23], v129 offset0:32 offset1:48
	ds_read2_b32 v[152:153], v129 offset0:164 offset1:180
	ds_read2_b32 v[24:25], v138 offset0:40 offset1:56
	ds_read2_b32 v[154:155], v138 offset0:172 offset1:188
	ds_read2_b32 v[18:19], v139 offset0:64 offset1:80
	ds_read2_b32 v[156:157], v139 offset0:196 offset1:212
	ds_read2_b32 v[20:21], v140 offset0:72 offset1:88
	ds_read2_b32 v[158:159], v140 offset0:204 offset1:220
	ds_read2_b32 v[14:15], v139 offset0:96 offset1:112
	ds_read2_b32 v[160:161], v139 offset0:228 offset1:244
	ds_read2_b32 v[16:17], v140 offset0:104 offset1:120
	ds_read2_b32 v[162:163], v140 offset0:236 offset1:252
	ds_read2_b32 v[10:11], v141 offset0:128 offset1:144
	ds_read2_b32 v[164:165], v142 offset0:4 offset1:20
	ds_read2_b32 v[12:13], v142 offset0:136 offset1:152
	ds_read2_b32 v[166:167], v143 offset0:12 offset1:28
	ds_read2_b32 v[6:7], v141 offset0:160 offset1:176
	ds_read2_b32 v[168:169], v142 offset0:36 offset1:52
	ds_read2_b32 v[8:9], v142 offset0:168 offset1:184
	ds_read2_b32 v[170:171], v143 offset0:44 offset1:60
	ds_read2_b32 v[2:3], v144 offset0:192 offset1:208
	ds_read2_b32 v[172:173], v145 offset0:68 offset1:84
	ds_read2_b32 v[4:5], v145 offset0:200 offset1:216
	ds_read2_b32 v[174:175], v146 offset0:76 offset1:92
	ds_read2_b32 v[30:31], v144 offset0:224 offset1:240
	ds_read2_b32 v[176:177], v145 offset0:100 offset1:116
	ds_read2_b32 v[32:33], v145 offset0:232 offset1:248
	ds_read2_b32 v[178:179], v146 offset0:108 offset1:124
	s_waitcnt lgkmcnt(0)
	s_barrier
	v_mov_b32_e32 v94, v31
	v_mov_b32_e32 v95, v177
	v_mov_b32_e32 v96, v33
	v_mov_b32_e32 v97, v179
	v_mov_b32_e32 v31, v176
	v_mov_b32_e32 v33, v178
	v_mov_b32_e32 v66, v3
	v_mov_b32_e32 v67, v173
	v_mov_b32_e32 v68, v5
	v_mov_b32_e32 v69, v175
	v_mov_b32_e32 v3, v172
	v_mov_b32_e32 v5, v174
	v_mov_b32_e32 v70, v7
	v_mov_b32_e32 v71, v169
	v_mov_b32_e32 v72, v9
	v_mov_b32_e32 v73, v171
	v_mov_b32_e32 v7, v168
	v_mov_b32_e32 v9, v170
	v_mov_b32_e32 v74, v11
	v_mov_b32_e32 v75, v165
	v_mov_b32_e32 v76, v13
	v_mov_b32_e32 v77, v167
	v_mov_b32_e32 v11, v164
	v_mov_b32_e32 v13, v166
	v_mov_b32_e32 v78, v15
	v_mov_b32_e32 v79, v161
	v_mov_b32_e32 v80, v17
	v_mov_b32_e32 v81, v163
	v_mov_b32_e32 v15, v160
	v_mov_b32_e32 v17, v162
	v_mov_b32_e32 v82, v19
	v_mov_b32_e32 v83, v157
	v_mov_b32_e32 v84, v21
	v_mov_b32_e32 v85, v159
	v_mov_b32_e32 v19, v156
	v_mov_b32_e32 v21, v158
	v_mov_b32_e32 v86, v23
	v_mov_b32_e32 v87, v153
	v_mov_b32_e32 v88, v25
	v_mov_b32_e32 v89, v155
	v_mov_b32_e32 v23, v152
	v_mov_b32_e32 v25, v154
	v_mov_b32_e32 v90, v27
	v_mov_b32_e32 v91, v149
	v_mov_b32_e32 v92, v29
	v_mov_b32_e32 v93, v151
	v_mov_b32_e32 v27, v148
	v_mov_b32_e32 v29, v150
	s_waitcnt lgkmcnt(0)
	s_barrier
	v_and_b32_e32 v174, 15, v0
	v_bfe_u32 v175, v0, 4, 2
	v_and_b32_e32 v111, 7, v174
	v_xor_b32_e32 v175, v175, v111
	v_lshlrev_b32_e32 v175, 4, v175
	v_lshl_or_b32 v175, v174, 7, v175
	v_bfe_u32 v174, v0, 7, 1
	v_lshl_or_b32 v100, v174, 13, v175
	v_bfe_u32 v174, v0, 6, 1
	v_lshl_or_b32 v168, v174, 13, v175
	v_or_b32_e32 v168, 0x4000, v168
	v_xor_b32_e32 v111, 64, v100
	v_xor_b32_e32 v169, 64, v168
	v_bfe_u32 v174, v0, 3, 3
	v_and_b32_e32 v175, 7, v0
	v_xor_b32_e32 v175, v175, v174
	v_lshlrev_b32_e32 v175, 4, v175
	v_lshl_or_b32 v175, v174, 11, v175
	v_lshrrev_b32_e32 v174, 6, v0
	v_and_b32_e32 v174, 3, v174
	v_lshl_or_b32 v170, v174, 16, v175
	v_add_u32_e32 v171, 0x3c00, v170
	v_add_u32_e32 v172, 0x7800, v170
	v_add_u32_e32 v173, 0xb400, v170
	v_lshlrev_b32_e32 v174, 12, v174
	s_nop 0
	v_readfirstlane_b32 s36, v174
	s_add_u32 s36, s36, 32
	v_mov_b32_e32 v116, 0
	v_mov_b32_e32 v117, 0
	v_mov_b32_e32 v118, 0
	v_mov_b32_e32 v119, 0
	v_mov_b32_e32 v120, 0
	v_mov_b32_e32 v121, 0
	v_mov_b32_e32 v122, 0
	v_mov_b32_e32 v123, 0
	v_mov_b32_e32 v124, 0
	v_mov_b32_e32 v125, 0
	v_mov_b32_e32 v126, 0
	v_mov_b32_e32 v127, 0
	v_mov_b32_e32 v148, 0
	v_mov_b32_e32 v149, 0
	v_mov_b32_e32 v150, 0
	v_mov_b32_e32 v151, 0
	v_mov_b32_e32 v152, 0
	v_mov_b32_e32 v153, 0
	v_mov_b32_e32 v154, 0
	v_mov_b32_e32 v155, 0
	v_mov_b32_e32 v156, 0
	v_mov_b32_e32 v157, 0
	v_mov_b32_e32 v158, 0
	v_mov_b32_e32 v159, 0
	v_mov_b32_e32 v160, 0
	v_mov_b32_e32 v161, 0
	v_mov_b32_e32 v162, 0
	v_mov_b32_e32 v163, 0
	v_mov_b32_e32 v164, 0
	v_mov_b32_e32 v165, 0
	v_mov_b32_e32 v166, 0
	v_mov_b32_e32 v167, 0
	s_waitcnt lgkmcnt(0)
	s_barrier
	v_readlane_b32 s98, v255, 16
	s_and_b32 s98, s98, 7
	s_lshl_b32 s98, s98, 1
	s_lshl_b32 s99, s98, 7
	s_add_u32 s6, s6, s99
	s_addc_u32 s7, s7, 0
	s_add_u32 s8, s8, s99
	s_addc_u32 s9, s9, 0
	s_add_u32 m0, s36, 0
	s_nop 0
	global_load_lds_dwordx4 v170, s[6:7] offset:0
	global_load_lds_dwordx4 v171, s[6:7] offset:1024
	global_load_lds_dwordx4 v172, s[6:7] offset:2048
	global_load_lds_dwordx4 v173, s[6:7] offset:3072
	s_add_u32 m0, s36, 16384
	s_nop 0
	global_load_lds_dwordx4 v170, s[8:9] offset:0
	global_load_lds_dwordx4 v171, s[8:9] offset:1024
	global_load_lds_dwordx4 v172, s[8:9] offset:2048
	global_load_lds_dwordx4 v173, s[8:9] offset:3072
	s_add_u32 s98, s98, 1
	s_and_b32 s98, s98, 15
	s_cmp_eq_u32 s98, 0
	s_cselect_b32 s99, 0x800, 0
	s_add_u32 s6, s6, 0x80
	s_addc_u32 s7, s7, 0
	s_sub_u32 s6, s6, s99
	s_subb_u32 s7, s7, 0
	s_add_u32 s8, s8, 0x80
	s_addc_u32 s9, s9, 0
	s_sub_u32 s8, s8, s99
	s_subb_u32 s9, s9, 0
	s_mov_b32 s5, 0
	s_waitcnt vmcnt(0)

.LBB0_1372:
	s_and_b32 s28, s11, 0xff
	s_mul_i32 s2, s28, 0xab
	s_lshr_b32 s29, s2, 11
	s_mul_i32 s2, s29, 12
	s_sub_i32 s2, s11, s2
	s_and_b32 s2, s2, 0xff
	s_lshl_b32 s2, s2, 21
	s_or_b32 s2, s2, s21
	s_add_u32 s14, s16, s2
	s_addc_u32 s15, s17, 0
	s_lshl_b32 s2, s29, 18
	s_add_u32 s12, s18, s2
	s_addc_u32 s13, s19, 0
	v_and_b32_e32 v162, 15, v0
	v_bfe_u32 v163, v0, 4, 2
	v_and_b32_e32 v107, 7, v162
	v_xor_b32_e32 v163, v163, v107
	v_lshlrev_b32_e32 v163, 4, v163
	v_lshl_or_b32 v163, v162, 7, v163
	v_bfe_u32 v162, v0, 7, 1
	v_lshl_or_b32 v98, v162, 13, v163
	v_bfe_u32 v162, v0, 6, 1
	v_lshl_or_b32 v156, v162, 13, v163
	v_or_b32_e32 v156, 0x4000, v156
	v_xor_b32_e32 v107, 64, v98
	v_xor_b32_e32 v157, 64, v156
	v_bfe_u32 v162, v0, 3, 3
	v_and_b32_e32 v163, 7, v0
	v_xor_b32_e32 v163, v163, v162
	v_lshlrev_b32_e32 v163, 4, v163
	v_lshl_or_b32 v163, v162, 11, v163
	v_lshrrev_b32_e32 v162, 6, v0
	v_and_b32_e32 v162, 3, v162
	v_lshl_or_b32 v158, v162, 16, v163
	v_add_u32_e32 v159, 0x3c00, v158
	v_add_u32_e32 v160, 0x7800, v158
	v_add_u32_e32 v161, 0xb400, v158
	v_lshlrev_b32_e32 v162, 12, v162
	s_nop 0
	v_readfirstlane_b32 s31, v162
	s_add_u32 s31, s31, 32
	v_mov_b32_e32 v94, 0
	v_mov_b32_e32 v95, 0
	v_mov_b32_e32 v96, 0
	v_mov_b32_e32 v97, 0
	v_mov_b32_e32 v90, 0
	v_mov_b32_e32 v91, 0
	v_mov_b32_e32 v92, 0
	v_mov_b32_e32 v93, 0
	v_mov_b32_e32 v82, 0
	v_mov_b32_e32 v83, 0
	v_mov_b32_e32 v84, 0
	v_mov_b32_e32 v85, 0
	v_mov_b32_e32 v78, 0
	v_mov_b32_e32 v79, 0
	v_mov_b32_e32 v80, 0
	v_mov_b32_e32 v81, 0
	v_mov_b32_e32 v74, 0
	v_mov_b32_e32 v75, 0
	v_mov_b32_e32 v76, 0
	v_mov_b32_e32 v77, 0
	v_mov_b32_e32 v70, 0
	v_mov_b32_e32 v71, 0
	v_mov_b32_e32 v72, 0
	v_mov_b32_e32 v73, 0
	v_mov_b32_e32 v66, 0
	v_mov_b32_e32 v67, 0
	v_mov_b32_e32 v68, 0
	v_mov_b32_e32 v69, 0
	v_mov_b32_e32 v62, 0
	v_mov_b32_e32 v63, 0
	v_mov_b32_e32 v64, 0
	v_mov_b32_e32 v65, 0
	v_mov_b32_e32 v58, 0
	v_mov_b32_e32 v59, 0
	v_mov_b32_e32 v60, 0
	v_mov_b32_e32 v61, 0
	v_mov_b32_e32 v42, 0
	v_mov_b32_e32 v43, 0
	v_mov_b32_e32 v44, 0
	v_mov_b32_e32 v45, 0
	v_mov_b32_e32 v22, 0
	v_mov_b32_e32 v23, 0
	v_mov_b32_e32 v24, 0
	v_mov_b32_e32 v25, 0
	v_mov_b32_e32 v14, 0
	v_mov_b32_e32 v15, 0
	v_mov_b32_e32 v16, 0
	v_mov_b32_e32 v17, 0
	v_mov_b32_e32 v10, 0
	v_mov_b32_e32 v11, 0
	v_mov_b32_e32 v12, 0
	v_mov_b32_e32 v13, 0
	v_mov_b32_e32 v6, 0
	v_mov_b32_e32 v7, 0
	v_mov_b32_e32 v8, 0
	v_mov_b32_e32 v9, 0
	v_mov_b32_e32 v2, 0
	v_mov_b32_e32 v3, 0
	v_mov_b32_e32 v4, 0
	v_mov_b32_e32 v5, 0
	v_mov_b32_e32 v86, 0
	v_mov_b32_e32 v87, 0
	v_mov_b32_e32 v88, 0
	v_mov_b32_e32 v89, 0
	v_mov_b32_e32 v108, 0
	v_mov_b32_e32 v109, 0
	v_mov_b32_e32 v110, 0
	v_mov_b32_e32 v111, 0
	v_mov_b32_e32 v112, 0
	v_mov_b32_e32 v113, 0
	v_mov_b32_e32 v114, 0
	v_mov_b32_e32 v115, 0
	v_mov_b32_e32 v116, 0
	v_mov_b32_e32 v117, 0
	v_mov_b32_e32 v118, 0
	v_mov_b32_e32 v119, 0
	v_mov_b32_e32 v136, 0
	v_mov_b32_e32 v137, 0
	v_mov_b32_e32 v138, 0
	v_mov_b32_e32 v139, 0
	v_mov_b32_e32 v140, 0
	v_mov_b32_e32 v141, 0
	v_mov_b32_e32 v142, 0
	v_mov_b32_e32 v143, 0
	v_mov_b32_e32 v144, 0
	v_mov_b32_e32 v145, 0
	v_mov_b32_e32 v146, 0
	v_mov_b32_e32 v147, 0
	v_mov_b32_e32 v148, 0
	v_mov_b32_e32 v149, 0
	v_mov_b32_e32 v150, 0
	v_mov_b32_e32 v151, 0
	v_mov_b32_e32 v152, 0
	v_mov_b32_e32 v153, 0
	v_mov_b32_e32 v154, 0
	v_mov_b32_e32 v155, 0
	s_waitcnt lgkmcnt(0)
	s_barrier
	v_readlane_b32 s98, v255, 16
	s_and_b32 s98, s98, 7
	s_lshl_b32 s98, s98, 1
	s_lshl_b32 s99, s98, 7
	s_add_u32 s14, s14, s99
	s_addc_u32 s15, s15, 0
	s_add_u32 s12, s12, s99
	s_addc_u32 s13, s13, 0
	s_add_u32 m0, s31, 0
	s_nop 0
	global_load_lds_dwordx4 v158, s[14:15] offset:0
	global_load_lds_dwordx4 v159, s[14:15] offset:1024
	global_load_lds_dwordx4 v160, s[14:15] offset:2048
	global_load_lds_dwordx4 v161, s[14:15] offset:3072
	s_add_u32 m0, s31, 16384
	s_nop 0
	global_load_lds_dwordx4 v158, s[12:13] offset:0
	global_load_lds_dwordx4 v159, s[12:13] offset:1024
	global_load_lds_dwordx4 v160, s[12:13] offset:2048
	global_load_lds_dwordx4 v161, s[12:13] offset:3072
	s_add_u32 s98, s98, 1
	s_and_b32 s98, s98, 15
	s_cmp_eq_u32 s98, 0
	s_cselect_b32 s99, 0x800, 0
	s_add_u32 s14, s14, 0x80
	s_addc_u32 s15, s15, 0
	s_sub_u32 s14, s14, s99
	s_subb_u32 s15, s15, 0
	s_add_u32 s12, s12, 0x80
	s_addc_u32 s13, s13, 0
	s_sub_u32 s12, s12, s99
	s_subb_u32 s13, s13, 0
	s_mov_b32 s30, 0
	s_waitcnt vmcnt(0)

.LBB0_1496:
	s_lshl_b32 s10, s50, 7
	s_or_b32 s46, s37, s10
	s_xor_b64 s[48:49], s[52:53], -1
	s_lshl_b64 s[52:53], s[46:47], 11
	s_add_u32 s52, s55, s52
	s_addc_u32 s53, s56, s53
	s_waitcnt lgkmcnt(0)
	s_lshl_b32 s98, s36, 11
	s_add_u32 s98, s33, s98
	s_addc_u32 s99, s54, 0
	v_and_b32_e32 v212, 15, v0
	v_bfe_u32 v213, v0, 4, 2
	v_and_b32_e32 v139, 7, v212
	v_xor_b32_e32 v213, v213, v139
	v_lshlrev_b32_e32 v213, 4, v213
	v_lshl_or_b32 v213, v212, 7, v213
	v_bfe_u32 v212, v0, 7, 1
	v_lshl_or_b32 v138, v212, 13, v213
	v_bfe_u32 v212, v0, 6, 1
	v_lshl_or_b32 v206, v212, 13, v213
	v_or_b32_e32 v206, 0x4000, v206
	v_xor_b32_e32 v139, 64, v138
	v_xor_b32_e32 v207, 64, v206
	v_bfe_u32 v212, v0, 3, 3
	v_and_b32_e32 v213, 7, v0
	v_xor_b32_e32 v213, v213, v212
	v_lshlrev_b32_e32 v213, 4, v213
	v_lshl_or_b32 v213, v212, 11, v213
	v_lshrrev_b32_e32 v212, 6, v0
	v_and_b32_e32 v212, 3, v212
	v_lshl_or_b32 v208, v212, 16, v213
	v_add_u32_e32 v209, 0x3c00, v208
	v_add_u32_e32 v210, 0x7800, v208
	v_add_u32_e32 v211, 0xb400, v208
	v_lshlrev_b32_e32 v212, 12, v212
	s_nop 0
	v_readfirstlane_b32 s101, v212
	s_add_u32 s101, s101, 32
	v_mov_b32_e32 v66, 0
	v_mov_b32_e32 v67, 0
	v_mov_b32_e32 v68, 0
	v_mov_b32_e32 v69, 0
	v_mov_b32_e32 v58, 0
	v_mov_b32_e32 v59, 0
	v_mov_b32_e32 v60, 0
	v_mov_b32_e32 v61, 0
	v_mov_b32_e32 v54, 0
	v_mov_b32_e32 v55, 0
	v_mov_b32_e32 v56, 0
	v_mov_b32_e32 v57, 0
	v_mov_b32_e32 v50, 0
	v_mov_b32_e32 v51, 0
	v_mov_b32_e32 v52, 0
	v_mov_b32_e32 v53, 0
	v_mov_b32_e32 v46, 0
	v_mov_b32_e32 v47, 0
	v_mov_b32_e32 v48, 0
	v_mov_b32_e32 v49, 0
	v_mov_b32_e32 v42, 0
	v_mov_b32_e32 v43, 0
	v_mov_b32_e32 v44, 0
	v_mov_b32_e32 v45, 0
	v_mov_b32_e32 v38, 0
	v_mov_b32_e32 v39, 0
	v_mov_b32_e32 v40, 0
	v_mov_b32_e32 v41, 0
	v_mov_b32_e32 v6, 0
	v_mov_b32_e32 v7, 0
	v_mov_b32_e32 v8, 0
	v_mov_b32_e32 v9, 0
	v_mov_b32_e32 v2, 0
	v_mov_b32_e32 v3, 0
	v_mov_b32_e32 v4, 0
	v_mov_b32_e32 v5, 0
	v_mov_b32_e32 v22, 0
	v_mov_b32_e32 v23, 0
	v_mov_b32_e32 v24, 0
	v_mov_b32_e32 v25, 0
	v_mov_b32_e32 v18, 0
	v_mov_b32_e32 v19, 0
	v_mov_b32_e32 v20, 0
	v_mov_b32_e32 v21, 0
	v_mov_b32_e32 v14, 0
	v_mov_b32_e32 v15, 0
	v_mov_b32_e32 v16, 0
	v_mov_b32_e32 v17, 0
	v_mov_b32_e32 v10, 0
	v_mov_b32_e32 v11, 0
	v_mov_b32_e32 v12, 0
	v_mov_b32_e32 v13, 0
	v_mov_b32_e32 v34, 0
	v_mov_b32_e32 v35, 0
	v_mov_b32_e32 v36, 0
	v_mov_b32_e32 v37, 0
	v_mov_b32_e32 v30, 0
	v_mov_b32_e32 v31, 0
	v_mov_b32_e32 v32, 0
	v_mov_b32_e32 v33, 0
	v_mov_b32_e32 v26, 0
	v_mov_b32_e32 v27, 0
	v_mov_b32_e32 v28, 0
	v_mov_b32_e32 v29, 0
	v_mov_b32_e32 v134, 0
	v_mov_b32_e32 v135, 0
	v_mov_b32_e32 v136, 0
	v_mov_b32_e32 v137, 0
	v_mov_b32_e32 v178, 0
	v_mov_b32_e32 v179, 0
	v_mov_b32_e32 v180, 0
	v_mov_b32_e32 v181, 0
	v_mov_b32_e32 v182, 0
	v_mov_b32_e32 v183, 0
	v_mov_b32_e32 v184, 0
	v_mov_b32_e32 v185, 0
	v_mov_b32_e32 v186, 0
	v_mov_b32_e32 v187, 0
	v_mov_b32_e32 v188, 0
	v_mov_b32_e32 v189, 0
	v_mov_b32_e32 v190, 0
	v_mov_b32_e32 v191, 0
	v_mov_b32_e32 v192, 0
	v_mov_b32_e32 v193, 0
	v_mov_b32_e32 v194, 0
	v_mov_b32_e32 v195, 0
	v_mov_b32_e32 v196, 0
	v_mov_b32_e32 v197, 0
	v_mov_b32_e32 v198, 0
	v_mov_b32_e32 v199, 0
	v_mov_b32_e32 v200, 0
	v_mov_b32_e32 v201, 0
	v_mov_b32_e32 v202, 0
	v_mov_b32_e32 v203, 0
	v_mov_b32_e32 v204, 0
	v_mov_b32_e32 v205, 0
	s_waitcnt lgkmcnt(0)
	s_barrier
	v_readlane_b32 s46, v255, 16
	s_and_b32 s46, s46, 7
	s_lshl_b32 s46, s46, 1
	s_lshl_b32 s51, s46, 7
	s_add_u32 s98, s98, s51
	s_addc_u32 s99, s99, 0
	s_add_u32 s52, s52, s51
	s_addc_u32 s53, s53, 0
	s_add_u32 m0, s101, 0
	s_nop 0
	global_load_lds_dwordx4 v208, s[98:99] offset:0
	global_load_lds_dwordx4 v209, s[98:99] offset:1024
	global_load_lds_dwordx4 v210, s[98:99] offset:2048
	global_load_lds_dwordx4 v211, s[98:99] offset:3072
	s_add_u32 m0, s101, 16384
	s_nop 0
	global_load_lds_dwordx4 v208, s[52:53] offset:0
	global_load_lds_dwordx4 v209, s[52:53] offset:1024
	global_load_lds_dwordx4 v210, s[52:53] offset:2048
	global_load_lds_dwordx4 v211, s[52:53] offset:3072
	s_add_u32 s46, s46, 1
	s_and_b32 s46, s46, 15
	s_cmp_eq_u32 s46, 0
	s_cselect_b32 s51, 0x800, 0
	s_add_u32 s98, s98, 0x80
	s_addc_u32 s99, s99, 0
	s_sub_u32 s98, s98, s51
	s_subb_u32 s99, s99, 0
	s_add_u32 s52, s52, 0x80
	s_addc_u32 s53, s53, 0
	s_sub_u32 s52, s52, s51
	s_subb_u32 s53, s53, 0
	s_mov_b32 s100, 0
	s_waitcnt vmcnt(0)
